# P1 GEMM: keep the two wave-halves staggered through the epilogue (ALIGN barrier only after the last unit)
# baseline (speedup 1.0000x reference)
.LBB0_105:
	s_add_u32 s30, s0, 0xfff80080
	s_addc_u32 s31, s1, -1
	s_add_i32 s63, 0, 0x10000
	s_cmp_eq_u32 s62, 28
	s_cselect_b32 s51, s41, s31
	s_cselect_b32 s50, s47, s30
	v_add_u32_e32 v150, s63, v153
	s_cselect_b32 s49, s39, s61
	s_cselect_b32 s48, s55, s60
	s_add_i32 s64, 0, 0x14000
	ds_read_b128 v[146:149], v150
	ds_read_b128 v[156:159], v150 offset:1024
	ds_read_b128 v[160:163], v150 offset:2048
	ds_read_b128 v[174:177], v150 offset:3072
	v_add_u32_e32 v150, s64, v153
	ds_read_b128 v[178:181], v150
	ds_read_b128 v[182:185], v150 offset:1024
	ds_read_b128 v[186:189], v150 offset:2048
	ds_read_b128 v[190:193], v150 offset:3072
	v_lshl_add_u64 v[150:151], s[0:1], 0, v[144:145]
	s_add_i32 m0, s9, 0xc000
	ds_read_b128 v[194:197], v155
	ds_read_b128 v[198:201], v155 offset:1024
	ds_read_b128 v[202:205], v155 offset:2048
	ds_read_b128 v[206:209], v155 offset:3072
	ds_read_b128 v[218:221], v155 offset:4096
	ds_read_b128 v[222:225], v155 offset:5120
	ds_read_b128 v[226:229], v155 offset:6144
	ds_read_b128 v[230:233], v155 offset:7168
	global_load_lds_dwordx4 v[150:151], off
	v_lshl_add_u64 v[150:151], s[0:1], 0, v[142:143]
	s_add_i32 m0, s9, 0xe000
	s_nop 0
	global_load_lds_dwordx4 v[150:151], off
	s_waitcnt vmcnt(8)
	s_waitcnt lgkmcnt(0)
	s_barrier
	s_setprio 1
	s_waitcnt lgkmcnt(0)
	v_mfma_f32_16x16x32_bf16 v[70:73], v[146:149], v[194:197], v[70:73]
	v_mfma_f32_16x16x32_bf16 v[66:69], v[160:163], v[194:197], v[66:69]
	v_mfma_f32_16x16x32_bf16 v[62:65], v[146:149], v[202:205], v[62:65]
	v_mfma_f32_16x16x32_bf16 v[58:61], v[160:163], v[202:205], v[58:61]
	v_mfma_f32_16x16x32_bf16 v[50:53], v[146:149], v[218:221], v[50:53]
	v_mfma_f32_16x16x32_bf16 v[46:49], v[160:163], v[218:221], v[46:49]
	v_mfma_f32_16x16x32_bf16 v[42:45], v[146:149], v[226:229], v[42:45]
	v_mfma_f32_16x16x32_bf16 v[38:41], v[160:163], v[226:229], v[38:41]
	v_mfma_f32_16x16x32_bf16 v[70:73], v[156:159], v[198:201], v[70:73]
	v_mfma_f32_16x16x32_bf16 v[66:69], v[174:177], v[198:201], v[66:69]
	v_mfma_f32_16x16x32_bf16 v[62:65], v[156:159], v[206:209], v[62:65]
	v_mfma_f32_16x16x32_bf16 v[58:61], v[174:177], v[206:209], v[58:61]
	v_mfma_f32_16x16x32_bf16 v[50:53], v[156:159], v[222:225], v[50:53]
	v_mfma_f32_16x16x32_bf16 v[46:49], v[174:177], v[222:225], v[46:49]
	v_mfma_f32_16x16x32_bf16 v[42:45], v[156:159], v[230:233], v[42:45]
	v_mfma_f32_16x16x32_bf16 v[38:41], v[174:177], v[230:233], v[38:41]
	s_setprio 0
	s_setprio 1
	v_mfma_f32_16x16x32_bf16 v[126:129], v[178:181], v[194:197], v[126:129]
	v_mfma_f32_16x16x32_bf16 v[122:125], v[186:189], v[194:197], v[122:125]
	v_mfma_f32_16x16x32_bf16 v[118:121], v[178:181], v[202:205], v[118:121]
	v_mfma_f32_16x16x32_bf16 v[114:117], v[186:189], v[202:205], v[114:117]
	v_mfma_f32_16x16x32_bf16 v[110:113], v[178:181], v[218:221], v[110:113]
	v_mfma_f32_16x16x32_bf16 v[106:109], v[186:189], v[218:221], v[106:109]
	v_mfma_f32_16x16x32_bf16 v[102:105], v[178:181], v[226:229], v[102:105]
	v_mfma_f32_16x16x32_bf16 v[98:101], v[186:189], v[226:229], v[98:101]
	v_mfma_f32_16x16x32_bf16 v[126:129], v[182:185], v[198:201], v[126:129]
	v_mfma_f32_16x16x32_bf16 v[122:125], v[190:193], v[198:201], v[122:125]
	v_mfma_f32_16x16x32_bf16 v[118:121], v[182:185], v[206:209], v[118:121]
	v_mfma_f32_16x16x32_bf16 v[114:117], v[190:193], v[206:209], v[114:117]
	v_mfma_f32_16x16x32_bf16 v[110:113], v[182:185], v[222:225], v[110:113]
	v_mfma_f32_16x16x32_bf16 v[106:109], v[190:193], v[222:225], v[106:109]
	v_mfma_f32_16x16x32_bf16 v[102:105], v[182:185], v[230:233], v[102:105]
	v_mfma_f32_16x16x32_bf16 v[98:101], v[190:193], v[230:233], v[98:101]
	s_setprio 0
	s_barrier
	s_add_i32 s30, s63, s8
	v_lshl_add_u64 v[150:151], s[48:49], 0, v[134:135]
	s_mov_b32 m0, s30
	ds_read_b128 v[194:197], v155 offset:16384
	ds_read_b128 v[198:201], v155 offset:17408
	ds_read_b128 v[202:205], v155 offset:18432
	ds_read_b128 v[206:209], v155 offset:19456
	ds_read_b128 v[218:221], v155 offset:20480
	ds_read_b128 v[222:225], v155 offset:21504
	ds_read_b128 v[226:229], v155 offset:22528
	ds_read_b128 v[230:233], v155 offset:23552
	global_load_lds_dwordx4 v[150:151], off
	s_add_i32 m0, s30, 0x2000
	s_add_u32 s30, s48, 0x80000
	v_lshl_add_u64 v[164:165], s[48:49], 0, v[130:131]
	s_addc_u32 s31, s49, 0
	s_add_i32 s63, s64, s8
	global_load_lds_dwordx4 v[164:165], off
	v_lshl_add_u64 v[166:167], s[30:31], 0, v[134:135]
	s_mov_b32 m0, s63
	v_lshl_add_u64 v[170:171], s[50:51], 0, v[132:133]
	global_load_lds_dwordx4 v[166:167], off
	v_lshl_add_u64 v[166:167], s[30:31], 0, v[130:131]
	s_add_i32 m0, s63, 0x2000
	s_nop 0
	global_load_lds_dwordx4 v[166:167], off
	v_lshl_add_u64 v[166:167], s[50:51], 0, v[136:137]
	s_mov_b32 m0, s9
	s_nop 0
	global_load_lds_dwordx4 v[166:167], off
	s_mov_b32 m0, s28
	s_nop 0
	global_load_lds_dwordx4 v[170:171], off
	s_waitcnt vmcnt(8)
	s_waitcnt lgkmcnt(0)
	s_barrier
	s_setprio 1
	s_waitcnt lgkmcnt(0)
	v_mfma_f32_16x16x32_bf16 v[30:33], v[146:149], v[194:197], v[30:33]
	v_mfma_f32_16x16x32_bf16 v[26:29], v[160:163], v[194:197], v[26:29]
	v_mfma_f32_16x16x32_bf16 v[22:25], v[146:149], v[202:205], v[22:25]
	v_mfma_f32_16x16x32_bf16 v[18:21], v[160:163], v[202:205], v[18:21]
	v_mfma_f32_16x16x32_bf16 v[14:17], v[146:149], v[218:221], v[14:17]
	v_mfma_f32_16x16x32_bf16 v[10:13], v[160:163], v[218:221], v[10:13]
	v_mfma_f32_16x16x32_bf16 v[6:9], v[146:149], v[226:229], v[6:9]
	v_mfma_f32_16x16x32_bf16 v[2:5], v[160:163], v[226:229], v[2:5]
	v_mfma_f32_16x16x32_bf16 v[30:33], v[156:159], v[198:201], v[30:33]
	v_mfma_f32_16x16x32_bf16 v[26:29], v[174:177], v[198:201], v[26:29]
	v_mfma_f32_16x16x32_bf16 v[22:25], v[156:159], v[206:209], v[22:25]
	v_mfma_f32_16x16x32_bf16 v[18:21], v[174:177], v[206:209], v[18:21]
	v_mfma_f32_16x16x32_bf16 v[14:17], v[156:159], v[222:225], v[14:17]
	v_mfma_f32_16x16x32_bf16 v[10:13], v[174:177], v[222:225], v[10:13]
	v_mfma_f32_16x16x32_bf16 v[6:9], v[156:159], v[230:233], v[6:9]
	v_mfma_f32_16x16x32_bf16 v[2:5], v[174:177], v[230:233], v[2:5]
	s_setprio 0
	s_setprio 1
	v_mfma_f32_16x16x32_bf16 v[94:97], v[178:181], v[194:197], v[94:97]
	v_mfma_f32_16x16x32_bf16 v[90:93], v[186:189], v[194:197], v[90:93]
	v_mfma_f32_16x16x32_bf16 v[86:89], v[178:181], v[202:205], v[86:89]
	v_mfma_f32_16x16x32_bf16 v[82:85], v[186:189], v[202:205], v[82:85]
	v_mfma_f32_16x16x32_bf16 v[78:81], v[178:181], v[218:221], v[78:81]
	v_mfma_f32_16x16x32_bf16 v[74:77], v[186:189], v[218:221], v[74:77]
	v_mfma_f32_16x16x32_bf16 v[54:57], v[178:181], v[226:229], v[54:57]
	v_mfma_f32_16x16x32_bf16 v[34:37], v[186:189], v[226:229], v[34:37]
	v_mfma_f32_16x16x32_bf16 v[94:97], v[182:185], v[198:201], v[94:97]
	v_mfma_f32_16x16x32_bf16 v[90:93], v[190:193], v[198:201], v[90:93]
	v_mfma_f32_16x16x32_bf16 v[86:89], v[182:185], v[206:209], v[86:89]
	v_mfma_f32_16x16x32_bf16 v[82:85], v[190:193], v[206:209], v[82:85]
	v_mfma_f32_16x16x32_bf16 v[78:81], v[182:185], v[222:225], v[78:81]
	v_mfma_f32_16x16x32_bf16 v[74:77], v[190:193], v[222:225], v[74:77]
	v_mfma_f32_16x16x32_bf16 v[54:57], v[182:185], v[230:233], v[54:57]
	v_mfma_f32_16x16x32_bf16 v[34:37], v[190:193], v[230:233], v[34:37]
	s_setprio 0
	s_barrier
	s_add_i32 s63, 0, 0x18000
	v_add_u32_e32 v172, s63, v153
	s_add_i32 s64, 0, 0x1c000
	ds_read_b128 v[146:149], v172
	ds_read_b128 v[156:159], v172 offset:1024
	ds_read_b128 v[160:163], v172 offset:2048
	ds_read_b128 v[174:177], v172 offset:3072
	v_add_u32_e32 v172, s64, v153
	ds_read_b128 v[178:181], v172
	ds_read_b128 v[182:185], v172 offset:1024
	ds_read_b128 v[186:189], v172 offset:2048
	ds_read_b128 v[190:193], v172 offset:3072
	s_add_u32 s30, s50, 0x80000
	s_addc_u32 s31, s51, 0
	s_mov_b32 m0, s29
	v_lshl_add_u64 v[172:173], s[30:31], 0, v[136:137]
	ds_read_b128 v[194:197], v155 offset:32768
	ds_read_b128 v[198:201], v155 offset:33792
	ds_read_b128 v[202:205], v155 offset:34816
	ds_read_b128 v[206:209], v155 offset:35840
	ds_read_b128 v[218:221], v155 offset:36864
	ds_read_b128 v[222:225], v155 offset:37888
	ds_read_b128 v[226:229], v155 offset:38912
	ds_read_b128 v[230:233], v155 offset:39936
	global_load_lds_dwordx4 v[172:173], off
	v_lshl_add_u64 v[172:173], s[30:31], 0, v[132:133]
	s_mov_b32 m0, s35
	s_nop 0
	global_load_lds_dwordx4 v[172:173], off
	s_waitcnt vmcnt(8)
	s_waitcnt lgkmcnt(0)
	s_barrier
	s_setprio 1
	s_waitcnt lgkmcnt(0)
	v_mfma_f32_16x16x32_bf16 v[70:73], v[146:149], v[194:197], v[70:73]
	v_mfma_f32_16x16x32_bf16 v[66:69], v[160:163], v[194:197], v[66:69]
	v_mfma_f32_16x16x32_bf16 v[62:65], v[146:149], v[202:205], v[62:65]
	v_mfma_f32_16x16x32_bf16 v[58:61], v[160:163], v[202:205], v[58:61]
	v_mfma_f32_16x16x32_bf16 v[50:53], v[146:149], v[218:221], v[50:53]
	v_mfma_f32_16x16x32_bf16 v[46:49], v[160:163], v[218:221], v[46:49]
	v_mfma_f32_16x16x32_bf16 v[42:45], v[146:149], v[226:229], v[42:45]
	v_mfma_f32_16x16x32_bf16 v[38:41], v[160:163], v[226:229], v[38:41]
	v_mfma_f32_16x16x32_bf16 v[70:73], v[156:159], v[198:201], v[70:73]
	v_mfma_f32_16x16x32_bf16 v[66:69], v[174:177], v[198:201], v[66:69]
	v_mfma_f32_16x16x32_bf16 v[62:65], v[156:159], v[206:209], v[62:65]
	v_mfma_f32_16x16x32_bf16 v[58:61], v[174:177], v[206:209], v[58:61]
	v_mfma_f32_16x16x32_bf16 v[50:53], v[156:159], v[222:225], v[50:53]
	v_mfma_f32_16x16x32_bf16 v[46:49], v[174:177], v[222:225], v[46:49]
	v_mfma_f32_16x16x32_bf16 v[42:45], v[156:159], v[230:233], v[42:45]
	v_mfma_f32_16x16x32_bf16 v[38:41], v[174:177], v[230:233], v[38:41]
	s_setprio 0
	s_setprio 1
	v_mfma_f32_16x16x32_bf16 v[126:129], v[178:181], v[194:197], v[126:129]
	v_mfma_f32_16x16x32_bf16 v[122:125], v[186:189], v[194:197], v[122:125]
	v_mfma_f32_16x16x32_bf16 v[118:121], v[178:181], v[202:205], v[118:121]
	v_mfma_f32_16x16x32_bf16 v[114:117], v[186:189], v[202:205], v[114:117]
	v_mfma_f32_16x16x32_bf16 v[110:113], v[178:181], v[218:221], v[110:113]
	v_mfma_f32_16x16x32_bf16 v[106:109], v[186:189], v[218:221], v[106:109]
	v_mfma_f32_16x16x32_bf16 v[102:105], v[178:181], v[226:229], v[102:105]
	v_mfma_f32_16x16x32_bf16 v[98:101], v[186:189], v[226:229], v[98:101]
	v_mfma_f32_16x16x32_bf16 v[126:129], v[182:185], v[198:201], v[126:129]
	v_mfma_f32_16x16x32_bf16 v[122:125], v[190:193], v[198:201], v[122:125]
	v_mfma_f32_16x16x32_bf16 v[118:121], v[182:185], v[206:209], v[118:121]
	v_mfma_f32_16x16x32_bf16 v[114:117], v[190:193], v[206:209], v[114:117]
	v_mfma_f32_16x16x32_bf16 v[110:113], v[182:185], v[222:225], v[110:113]
	v_mfma_f32_16x16x32_bf16 v[106:109], v[190:193], v[222:225], v[106:109]
	v_mfma_f32_16x16x32_bf16 v[102:105], v[182:185], v[230:233], v[102:105]
	v_mfma_f32_16x16x32_bf16 v[98:101], v[190:193], v[230:233], v[98:101]
	s_setprio 0
	s_barrier
	s_add_i32 s30, s63, s8
	v_lshl_add_u64 v[150:151], v[150:151], 0, s[24:25]
	s_mov_b32 m0, s30
	ds_read_b128 v[194:197], v155 offset:49152
	ds_read_b128 v[198:201], v155 offset:50176
	ds_read_b128 v[202:205], v155 offset:51200
	ds_read_b128 v[206:209], v155 offset:52224
	ds_read_b128 v[218:221], v155 offset:53248
	ds_read_b128 v[222:225], v155 offset:54272
	ds_read_b128 v[226:229], v155 offset:55296
	ds_read_b128 v[230:233], v155 offset:56320
	global_load_lds_dwordx4 v[150:151], off
	s_add_i32 m0, s30, 0x2000
	s_add_u32 s30, s48, 0x80080
	v_lshl_add_u64 v[150:151], v[164:165], 0, s[24:25]
	s_addc_u32 s31, s49, 0
	s_add_i32 s48, s64, s8
	global_load_lds_dwordx4 v[150:151], off
	v_lshl_add_u64 v[150:151], s[30:31], 0, v[134:135]
	s_mov_b32 m0, s48
	s_nop 0
	global_load_lds_dwordx4 v[150:151], off
	v_lshl_add_u64 v[150:151], s[30:31], 0, v[130:131]
	s_add_i32 m0, s48, 0x2000
	s_nop 0
	global_load_lds_dwordx4 v[150:151], off
	v_lshl_add_u64 v[150:151], v[166:167], 0, s[24:25]
	s_mov_b32 m0, s52
	s_nop 0
	global_load_lds_dwordx4 v[150:151], off
	v_lshl_add_u64 v[150:151], v[170:171], 0, s[24:25]
	s_mov_b32 m0, s53
	s_nop 0
	global_load_lds_dwordx4 v[150:151], off
	s_waitcnt vmcnt(8)
	s_waitcnt lgkmcnt(0)
	s_barrier
	s_setprio 1
	s_waitcnt lgkmcnt(0)
	v_mfma_f32_16x16x32_bf16 v[30:33], v[146:149], v[194:197], v[30:33]
	v_mfma_f32_16x16x32_bf16 v[26:29], v[160:163], v[194:197], v[26:29]
	v_mfma_f32_16x16x32_bf16 v[22:25], v[146:149], v[202:205], v[22:25]
	v_mfma_f32_16x16x32_bf16 v[18:21], v[160:163], v[202:205], v[18:21]
	v_mfma_f32_16x16x32_bf16 v[14:17], v[146:149], v[218:221], v[14:17]
	v_mfma_f32_16x16x32_bf16 v[10:13], v[160:163], v[218:221], v[10:13]
	v_mfma_f32_16x16x32_bf16 v[6:9], v[146:149], v[226:229], v[6:9]
	v_mfma_f32_16x16x32_bf16 v[2:5], v[160:163], v[226:229], v[2:5]
	v_mfma_f32_16x16x32_bf16 v[30:33], v[156:159], v[198:201], v[30:33]
	v_mfma_f32_16x16x32_bf16 v[26:29], v[174:177], v[198:201], v[26:29]
	v_mfma_f32_16x16x32_bf16 v[22:25], v[156:159], v[206:209], v[22:25]
	v_mfma_f32_16x16x32_bf16 v[18:21], v[174:177], v[206:209], v[18:21]
	v_mfma_f32_16x16x32_bf16 v[14:17], v[156:159], v[222:225], v[14:17]
	v_mfma_f32_16x16x32_bf16 v[10:13], v[174:177], v[222:225], v[10:13]
	v_mfma_f32_16x16x32_bf16 v[6:9], v[156:159], v[230:233], v[6:9]
	v_mfma_f32_16x16x32_bf16 v[2:5], v[174:177], v[230:233], v[2:5]
	s_setprio 0
	s_setprio 1
	v_mfma_f32_16x16x32_bf16 v[94:97], v[178:181], v[194:197], v[94:97]
	v_mfma_f32_16x16x32_bf16 v[90:93], v[186:189], v[194:197], v[90:93]
	v_mfma_f32_16x16x32_bf16 v[86:89], v[178:181], v[202:205], v[86:89]
	v_mfma_f32_16x16x32_bf16 v[82:85], v[186:189], v[202:205], v[82:85]
	v_mfma_f32_16x16x32_bf16 v[78:81], v[178:181], v[218:221], v[78:81]
	v_mfma_f32_16x16x32_bf16 v[74:77], v[186:189], v[218:221], v[74:77]
	v_mfma_f32_16x16x32_bf16 v[54:57], v[178:181], v[226:229], v[54:57]
	v_mfma_f32_16x16x32_bf16 v[34:37], v[186:189], v[226:229], v[34:37]
	v_mfma_f32_16x16x32_bf16 v[94:97], v[182:185], v[198:201], v[94:97]
	v_mfma_f32_16x16x32_bf16 v[90:93], v[190:193], v[198:201], v[90:93]
	v_mfma_f32_16x16x32_bf16 v[86:89], v[182:185], v[206:209], v[86:89]
	v_mfma_f32_16x16x32_bf16 v[82:85], v[190:193], v[206:209], v[82:85]
	v_mfma_f32_16x16x32_bf16 v[78:81], v[182:185], v[222:225], v[78:81]
	v_mfma_f32_16x16x32_bf16 v[74:77], v[190:193], v[222:225], v[74:77]
	v_mfma_f32_16x16x32_bf16 v[54:57], v[182:185], v[230:233], v[54:57]
	v_mfma_f32_16x16x32_bf16 v[34:37], v[190:193], v[230:233], v[34:37]
	s_setprio 0
	s_barrier
	s_add_i32 s62, s62, 2
	s_add_u32 s60, s60, 0x100
	s_addc_u32 s61, s61, 0
	s_add_u32 s0, s0, 0x100
	s_addc_u32 s1, s1, 0
	s_cmp_gt_u32 s62, 29
	s_cbranch_scc0 .LBB0_105
	s_and_b64 vcc, exec, s[36:37]
	s_cbranch_vccnz .LBB0_108
	s_and_b64 vcc, exec, s[16:17]
	s_cbranch_vccz .LBB0_108
	s_barrier

.LBB0_119:
	s_branch .LBB0_100
